# m3: BOG output-gate loads and mng load issued at chunk top instead of in the rmsnorm tail
# baseline (speedup 1.0000x reference)
.LBB0_448:
	s_or_b64 exec, exec, s[2:3]
	v_bfe_u32 v3, v1, 16, 1
	s_movk_i32 s2, 0x7fff
	v_lshlrev_b32_e32 v2, 3, v4
	v_add3_u32 v1, v1, v3, s2
	ds_write_b16_d16_hi v0, v1 offset:60336
	v_mul_u32_u24_e32 v0, 0x90, v9
	v_lshlrev_b32_e32 v1, 1, v2
	s_waitcnt lgkmcnt(0)
	s_barrier
	v_add3_u32 v12, 0, v0, v1
	ds_read_b128 v[14:17], v10 offset:59904
	ds_read_b128 v[0:3], v12 offset:36864
	ds_read_b128 v[18:21], v10 offset:59968
	ds_read_b128 v[4:7], v12 offset:36928
	s_waitcnt lgkmcnt(2)
	v_mfma_f32_16x16x32_bf16 v[0:3], v[14:17], v[0:3], 0
	s_lshl_b32 s2, s4, 2
	s_add_i32 s2, s2, 0
	s_add_i32 s2, s2, 0x19200
	s_waitcnt lgkmcnt(0)
	v_mfma_f32_16x16x32_bf16 v[24:27], v[18:21], v[4:7], v[0:3]
	ds_read_b128 v[28:31], v10
	s_nop 1
	ds_read_b128 v[0:3], v12 offset:57600
	ds_read_b128 v[32:35], v10 offset:64
	ds_read_b128 v[4:7], v12 offset:57664
	s_ashr_i32 s3, s40, 6
	s_waitcnt lgkmcnt(2)
	v_mfma_f32_16x16x32_bf16 v[0:3], v[28:31], v[0:3], 0
	v_readlane_b32 s7, v254, 34
	s_waitcnt lgkmcnt(0)
	v_mfma_f32_16x16x32_bf16 v[36:39], v[32:35], v[4:7], v[0:3]
	s_nop 4
	v_and_b32_e32 v0, 48, v23
	v_add_u32_e32 v4, s2, v0
	v_and_or_b32 v0, v201, 64, v0
	v_lshlrev_b32_e32 v12, 2, v0
	ds_read_b128 v[0:3], v4 offset:512
	ds_read_b128 v[4:7], v4 offset:768
	s_lshl_b32 s2, s3, 4
	s_and_b32 s6, s2, 0xffffffc0
	v_or_b32_e32 v40, s6, v9
	s_waitcnt lgkmcnt(1)
	v_fma_f32 v13, v36, v0, v24
	v_fma_f32 v23, v37, v1, v25
	v_fma_f32 v24, v38, v2, v26
	v_fmac_f32_e32 v27, v39, v3
	v_mad_u64_u32 v[36:37], s[4:5], v40, s84, v[8:9]
	ds_bpermute_b32 v38, v12, v24
	ds_bpermute_b32 v39, v12, v27
	ds_read_b128 v[24:27], v36 offset:18432
	s_waitcnt lgkmcnt(0)
	v_mfma_f32_16x16x32_bf16 v[14:17], v[14:17], v[24:27], 0
	ds_read_b128 v[24:27], v36 offset:18496
	ds_bpermute_b32 v13, v12, v13
	v_max_f32_e32 v4, v4, v4
	s_waitcnt lgkmcnt(1)
	v_mfma_f32_16x16x32_bf16 v[14:17], v[18:21], v[24:27], v[14:17]
	ds_read_b128 v[18:21], v36 offset:39168
	ds_read_b128 v[24:27], v36 offset:39232
	s_waitcnt lgkmcnt(2)
	v_max_f32_e64 v13, |v13|, |v13|
	s_waitcnt lgkmcnt(1)
	v_mfma_f32_16x16x32_bf16 v[18:21], v[28:31], v[18:21], 0
	v_max_f32_e32 v4, v13, v4
	ds_bpermute_b32 v23, v12, v23
	v_lshl_add_u32 v12, v9, 2, s7
	s_waitcnt lgkmcnt(1)
	v_mfma_f32_16x16x32_bf16 v[18:21], v[32:35], v[24:27], v[18:21]
	v_lshl_add_u32 v24, s6, 2, v12
	s_movk_i32 s6, 0x210
	v_mad_u32_u24 v36, v11, s6, v24
	v_max_f32_e32 v5, v5, v5
	v_max_f32_e32 v6, v6, v6
	s_nop 2
	v_fma_f32 v14, v0, v18, v14
	v_div_scale_f32 v13, s[4:5], v4, v4, v14
	v_rcp_f32_e32 v18, v13
	v_max_f32_e32 v7, v7, v7
	v_fmac_f32_e32 v17, v3, v21
	s_or_b32 s2, s2, 48
	v_fma_f32 v25, -v13, v18, 1.0
	v_fmac_f32_e32 v18, v25, v18
	v_div_scale_f32 v25, vcc, v14, v4, v14
	v_mul_f32_e32 v26, v25, v18
	v_fma_f32 v27, -v13, v26, v25
	v_fmac_f32_e32 v26, v27, v18
	v_fma_f32 v13, -v13, v26, v25
	v_div_fmas_f32 v13, v13, v18, v26
	v_div_fixup_f32 v13, v13, v4, v14
	s_waitcnt lgkmcnt(0)
	v_max_f32_e64 v14, |v23|, |v23|
	ds_write_b32 v36, v13
	v_fma_f32 v13, v1, v19, v15
	v_max_f32_e32 v5, v14, v5
	v_div_scale_f32 v14, s[4:5], v5, v5, v13
	v_rcp_f32_e32 v15, v14
	s_nop 0
	v_fma_f32 v18, -v14, v15, 1.0
	v_fmac_f32_e32 v15, v18, v15
	v_div_scale_f32 v18, vcc, v13, v5, v13
	v_mul_f32_e32 v19, v18, v15
	v_fma_f32 v23, -v14, v19, v18
	v_fmac_f32_e32 v19, v23, v15
	v_fma_f32 v14, -v14, v19, v18
	v_div_fmas_f32 v14, v14, v15, v19
	v_div_fixup_f32 v14, v14, v5, v13
	v_mad_u32_u24 v13, v11, s6, s6
	v_add_u32_e32 v23, v24, v13
	v_max_f32_e64 v15, |v38|, |v38|
	ds_write_b32 v23, v14
	v_fma_f32 v14, v2, v20, v16
	v_max_f32_e32 v6, v15, v6
	v_div_scale_f32 v15, s[4:5], v6, v6, v14
	v_rcp_f32_e32 v16, v15
	s_nop 0
	v_fma_f32 v18, -v15, v16, 1.0
	v_fmac_f32_e32 v16, v18, v16
	v_div_scale_f32 v18, vcc, v14, v6, v14
	v_mul_f32_e32 v19, v18, v16
	v_fma_f32 v20, -v15, v19, v18
	v_fmac_f32_e32 v19, v20, v16
	v_fma_f32 v15, -v15, v19, v18
	v_div_fmas_f32 v15, v15, v16, v19
	v_div_fixup_f32 v15, v15, v6, v14
	v_mov_b32_e32 v14, 0x420
	v_mad_u32_u24 v14, v11, s6, v14
	v_add_u32_e32 v37, v24, v14
	ds_write_b32 v37, v15
	v_max_f32_e64 v15, |v39|, |v39|
	v_max_f32_e32 v7, v15, v7
	v_div_scale_f32 v15, s[4:5], v7, v7, v17
	v_rcp_f32_e32 v16, v15
	s_nop 0
	v_fma_f32 v18, -v15, v16, 1.0
	v_fmac_f32_e32 v16, v18, v16
	v_div_scale_f32 v18, vcc, v17, v7, v17
	v_mul_f32_e32 v19, v18, v16
	v_fma_f32 v20, -v15, v19, v18
	v_fmac_f32_e32 v19, v20, v16
	v_fma_f32 v15, -v15, v19, v18
	v_div_fmas_f32 v15, v15, v16, v19
	v_div_fixup_f32 v16, v15, v7, v17
	v_mad_u32_u24 v15, v11, s6, v206
	v_add_u32_e32 v38, v24, v15
	ds_write_b32 v38, v16
	v_or_b32_e32 v16, 16, v40
	v_mad_u64_u32 v[20:21], s[4:5], v16, s84, v[8:9]
	ds_read_b128 v[16:19], v10 offset:59904
	ds_read_b128 v[24:27], v20 offset:18432
	s_waitcnt lgkmcnt(0)
	v_mfma_f32_16x16x32_bf16 v[16:19], v[16:19], v[24:27], 0
	ds_read_b128 v[24:27], v10 offset:59968
	ds_read_b128 v[28:31], v20 offset:18496
	s_waitcnt lgkmcnt(0)
	v_mfma_f32_16x16x32_bf16 v[16:19], v[24:27], v[28:31], v[16:19]
	ds_read_b128 v[24:27], v10
	ds_read_b128 v[28:31], v20 offset:39168
	s_waitcnt lgkmcnt(0)
	v_mfma_f32_16x16x32_bf16 v[24:27], v[24:27], v[28:31], 0
	ds_read_b128 v[28:31], v10 offset:64
	ds_read_b128 v[32:35], v20 offset:39232
	s_waitcnt lgkmcnt(0)
	v_mfma_f32_16x16x32_bf16 v[24:27], v[28:31], v[32:35], v[24:27]
	s_nop 7
	v_fma_f32 v16, v0, v24, v16
	v_div_scale_f32 v20, s[4:5], v4, v4, v16
	v_rcp_f32_e32 v21, v20
	v_fmac_f32_e32 v19, v3, v27
	v_fma_f32 v24, -v20, v21, 1.0
	v_fmac_f32_e32 v21, v24, v21
	v_div_scale_f32 v24, vcc, v16, v4, v16
	v_mul_f32_e32 v28, v24, v21
	v_fma_f32 v29, -v20, v28, v24
	v_fmac_f32_e32 v28, v29, v21
	v_fma_f32 v20, -v20, v28, v24
	v_div_fmas_f32 v20, v20, v21, v28
	v_div_fixup_f32 v16, v20, v4, v16
	ds_write_b32 v36, v16 offset:64
	v_fma_f32 v16, v1, v25, v17
	v_div_scale_f32 v17, s[4:5], v5, v5, v16
	v_rcp_f32_e32 v20, v17
	s_nop 0
	v_fma_f32 v21, -v17, v20, 1.0
	v_fmac_f32_e32 v20, v21, v20
	v_div_scale_f32 v21, vcc, v16, v5, v16
	v_mul_f32_e32 v24, v21, v20
	v_fma_f32 v25, -v17, v24, v21
	v_fmac_f32_e32 v24, v25, v20
	v_fma_f32 v17, -v17, v24, v21
	v_div_fmas_f32 v17, v17, v20, v24
	v_div_fixup_f32 v16, v17, v5, v16
	ds_write_b32 v23, v16 offset:64
	v_fma_f32 v16, v2, v26, v18
	v_div_scale_f32 v17, s[4:5], v6, v6, v16
	v_rcp_f32_e32 v18, v17
	s_nop 0
	v_fma_f32 v20, -v17, v18, 1.0
	v_fmac_f32_e32 v18, v20, v18
	v_div_scale_f32 v20, vcc, v16, v6, v16
	v_mul_f32_e32 v21, v20, v18
	v_fma_f32 v24, -v17, v21, v20
	v_fmac_f32_e32 v21, v24, v18
	v_fma_f32 v17, -v17, v21, v20
	v_div_fmas_f32 v17, v17, v18, v21
	v_div_fixup_f32 v16, v17, v6, v16
	ds_write_b32 v37, v16 offset:64
	v_div_scale_f32 v16, s[4:5], v7, v7, v19
	v_rcp_f32_e32 v17, v16
	s_nop 0
	v_fma_f32 v18, -v16, v17, 1.0
	v_fmac_f32_e32 v17, v18, v17
	v_div_scale_f32 v18, vcc, v19, v7, v19
	v_mul_f32_e32 v20, v18, v17
	v_fma_f32 v21, -v16, v20, v18
	v_fmac_f32_e32 v20, v21, v17
	v_fma_f32 v16, -v16, v20, v18
	v_div_fmas_f32 v16, v16, v17, v20
	v_div_fixup_f32 v16, v16, v7, v19
	ds_write_b32 v38, v16 offset:64
	v_or_b32_e32 v16, 32, v40
	v_mad_u64_u32 v[20:21], s[4:5], v16, s84, v[8:9]
	ds_read_b128 v[16:19], v10 offset:59904
	ds_read_b128 v[24:27], v20 offset:18432
	s_waitcnt lgkmcnt(0)
	v_mfma_f32_16x16x32_bf16 v[16:19], v[16:19], v[24:27], 0
	ds_read_b128 v[24:27], v10 offset:59968
	ds_read_b128 v[28:31], v20 offset:18496
	v_or_b32_e32 v9, s2, v9
	v_mad_u64_u32 v[8:9], s[4:5], v9, s84, v[8:9]
	s_waitcnt lgkmcnt(0)
	v_mfma_f32_16x16x32_bf16 v[16:19], v[24:27], v[28:31], v[16:19]
	ds_read_b128 v[24:27], v10
	ds_read_b128 v[28:31], v20 offset:39168
	s_waitcnt lgkmcnt(0)
	v_mfma_f32_16x16x32_bf16 v[24:27], v[24:27], v[28:31], 0
	ds_read_b128 v[28:31], v10 offset:64
	ds_read_b128 v[32:35], v20 offset:39232
	s_waitcnt lgkmcnt(0)
	v_mfma_f32_16x16x32_bf16 v[24:27], v[28:31], v[32:35], v[24:27]
	s_nop 7
	v_fma_f32 v16, v0, v24, v16
	v_div_scale_f32 v20, s[4:5], v4, v4, v16
	v_rcp_f32_e32 v21, v20
	v_fmac_f32_e32 v19, v3, v27
	v_fma_f32 v24, -v20, v21, 1.0
	v_fmac_f32_e32 v21, v24, v21
	v_div_scale_f32 v24, vcc, v16, v4, v16
	v_mul_f32_e32 v28, v24, v21
	v_fma_f32 v29, -v20, v28, v24
	v_fmac_f32_e32 v28, v29, v21
	v_fma_f32 v20, -v20, v28, v24
	v_div_fmas_f32 v20, v20, v21, v28
	v_div_fixup_f32 v16, v20, v4, v16
	ds_write_b32 v36, v16 offset:128
	v_fma_f32 v16, v1, v25, v17
	v_div_scale_f32 v17, s[4:5], v5, v5, v16
	v_rcp_f32_e32 v20, v17
	s_nop 0
	v_fma_f32 v21, -v17, v20, 1.0
	v_fmac_f32_e32 v20, v21, v20
	v_div_scale_f32 v21, vcc, v16, v5, v16
	v_mul_f32_e32 v24, v21, v20
	v_fma_f32 v25, -v17, v24, v21
	v_fmac_f32_e32 v24, v25, v20
	v_fma_f32 v17, -v17, v24, v21
	v_div_fmas_f32 v17, v17, v20, v24
	v_div_fixup_f32 v16, v17, v5, v16
	ds_write_b32 v23, v16 offset:128
	v_fma_f32 v16, v2, v26, v18
	v_div_scale_f32 v17, s[4:5], v6, v6, v16
	v_rcp_f32_e32 v18, v17
	s_nop 0
	v_fma_f32 v20, -v17, v18, 1.0
	v_fmac_f32_e32 v18, v20, v18
	v_div_scale_f32 v20, vcc, v16, v6, v16
	v_mul_f32_e32 v21, v20, v18
	v_fma_f32 v23, -v17, v21, v20
	v_fmac_f32_e32 v21, v23, v18
	v_fma_f32 v17, -v17, v21, v20
	v_div_fmas_f32 v17, v17, v18, v21
	v_div_fixup_f32 v16, v17, v6, v16
	ds_write_b32 v37, v16 offset:128
	v_div_scale_f32 v16, s[4:5], v7, v7, v19
	v_rcp_f32_e32 v17, v16
	s_nop 0
	v_fma_f32 v18, -v16, v17, 1.0
	v_fmac_f32_e32 v17, v18, v17
	v_div_scale_f32 v18, vcc, v19, v7, v19
	v_mul_f32_e32 v20, v18, v17
	v_fma_f32 v21, -v16, v20, v18
	v_fmac_f32_e32 v20, v21, v17
	v_fma_f32 v16, -v16, v20, v18
	v_div_fmas_f32 v16, v16, v17, v20
	v_div_fixup_f32 v16, v16, v7, v19
	ds_write_b32 v38, v16 offset:128
	ds_read_b128 v[16:19], v10 offset:59904
	ds_read_b128 v[24:27], v8 offset:18432
	s_waitcnt lgkmcnt(0)
	v_mfma_f32_16x16x32_bf16 v[16:19], v[16:19], v[24:27], 0
	ds_read_b128 v[24:27], v10 offset:59968
	ds_read_b128 v[28:31], v8 offset:18496
	s_waitcnt lgkmcnt(0)
	v_mfma_f32_16x16x32_bf16 v[16:19], v[24:27], v[28:31], v[16:19]
	ds_read_b128 v[24:27], v10
	ds_read_b128 v[28:31], v8 offset:39168
	s_waitcnt lgkmcnt(0)
	v_mfma_f32_16x16x32_bf16 v[24:27], v[24:27], v[28:31], 0
	ds_read_b128 v[28:31], v10 offset:64
	ds_read_b128 v[32:35], v8 offset:39232
	v_lshl_add_u32 v8, s2, 2, v12
	s_lshl_b32 s2, s3, 3
	s_waitcnt lgkmcnt(0)
	v_mfma_f32_16x16x32_bf16 v[24:27], v[28:31], v[32:35], v[24:27]
	s_mulk_i32 s3, 0x1080
	s_nop 6
	v_fma_f32 v0, v0, v24, v16
	v_div_scale_f32 v9, s[4:5], v4, v4, v0
	v_rcp_f32_e32 v10, v9
	v_fmac_f32_e32 v19, v3, v27
	v_fma_f32 v12, -v9, v10, 1.0
	v_fmac_f32_e32 v10, v12, v10
	v_div_scale_f32 v12, vcc, v0, v4, v0
	v_mul_f32_e32 v16, v12, v10
	v_fma_f32 v20, -v9, v16, v12
	v_fmac_f32_e32 v16, v20, v10
	v_fma_f32 v9, -v9, v16, v12
	v_div_fmas_f32 v9, v9, v10, v16
	v_div_fixup_f32 v0, v9, v4, v0
	v_mad_u32_u24 v4, v11, s6, v8
	ds_write_b32 v4, v0
	v_fma_f32 v0, v1, v25, v17
	v_div_scale_f32 v1, s[4:5], v5, v5, v0
	v_rcp_f32_e32 v4, v1
	s_nop 0
	v_fma_f32 v9, -v1, v4, 1.0
	v_fmac_f32_e32 v4, v9, v4
	v_div_scale_f32 v9, vcc, v0, v5, v0
	v_mul_f32_e32 v10, v9, v4
	v_fma_f32 v11, -v1, v10, v9
	v_fmac_f32_e32 v10, v11, v4
	v_fma_f32 v1, -v1, v10, v9
	v_div_fmas_f32 v1, v1, v4, v10
	v_div_fixup_f32 v0, v1, v5, v0
	v_add_u32_e32 v1, v8, v13
	ds_write_b32 v1, v0
	v_fma_f32 v0, v2, v26, v18
	v_div_scale_f32 v1, s[4:5], v6, v6, v0
	v_rcp_f32_e32 v2, v1
	s_nop 0
	v_fma_f32 v4, -v1, v2, 1.0
	v_fmac_f32_e32 v2, v4, v2
	v_div_scale_f32 v4, vcc, v0, v6, v0
	v_mul_f32_e32 v5, v4, v2
	v_fma_f32 v9, -v1, v5, v4
	v_fmac_f32_e32 v5, v9, v2
	v_fma_f32 v1, -v1, v5, v4
	v_div_fmas_f32 v1, v1, v2, v5
	v_div_fixup_f32 v0, v1, v6, v0
	v_add_u32_e32 v1, v8, v14
	ds_write_b32 v1, v0
	v_div_scale_f32 v0, s[4:5], v7, v7, v19
	v_rcp_f32_e32 v1, v0
	s_nop 0
	v_fma_f32 v2, -v0, v1, 1.0
	v_fmac_f32_e32 v1, v2, v1
	v_div_scale_f32 v2, vcc, v19, v7, v19
	v_mul_f32_e32 v3, v2, v1
	v_fma_f32 v4, -v0, v3, v2
	v_fmac_f32_e32 v3, v4, v1
	v_fma_f32 v0, -v0, v3, v2
	v_lshlrev_b32_e32 v2, 3, v22
	v_div_fmas_f32 v0, v0, v1, v3
	v_add_u32_e32 v10, s7, v2
	v_div_fixup_f32 v0, v0, v7, v19
	v_add_u32_e32 v1, v8, v15
	v_add_u32_e32 v6, s3, v10
	ds_write_b32 v1, v0
	s_waitcnt lgkmcnt(0)
	s_barrier
	s_add_u32 s4, s34, s2
	s_addc_u32 s5, s35, 0
	s_lshl_b64 s[4:5], s[4:5], 11
	s_lshl_b32 s3, s12, 1
	v_lshl_or_b32 v3, v22, 2, s3
	ds_read_b64 v[48:49], v6
	ds_read_b64 v[50:51], v6 offset:528
	ds_read_b64 v[52:53], v6 offset:1056
	ds_read_b64 v[54:55], v6 offset:1584
	ds_read_b64 v[56:57], v6 offset:2112
	ds_read_b64 v[58:59], v6 offset:2640
	ds_read_b64 v[60:61], v6 offset:3168
	ds_read_b64 v[62:63], v6 offset:3696
	s_add_u32 s98, s24, s4
	s_addc_u32 s99, s25, s5
	v_lshlrev_b32_e32 v90, 2, v201
	v_xor_b32_e32 v91, 4, v90
	v_xor_b32_e32 v92, 8, v90
	v_xor_b32_e32 v93, 16, v90
	v_xor_b32_e32 v94, 32, v90
	v_xor_b32_e32 v95, 64, v90
	v_xor_b32_e32 v96, 0x80, v90
	s_waitcnt lgkmcnt(0)
	v_pk_mul_f32 v[98:99], v[48:49], v[48:49]
	v_add_f32_e32 v64, v98, v99
	v_pk_mul_f32 v[98:99], v[50:51], v[50:51]
	v_add_f32_e32 v65, v98, v99
	v_pk_mul_f32 v[98:99], v[52:53], v[52:53]
	v_add_f32_e32 v66, v98, v99
	v_pk_mul_f32 v[98:99], v[54:55], v[54:55]
	v_add_f32_e32 v67, v98, v99
	v_pk_mul_f32 v[98:99], v[56:57], v[56:57]
	v_add_f32_e32 v68, v98, v99
	v_pk_mul_f32 v[98:99], v[58:59], v[58:59]
	v_add_f32_e32 v69, v98, v99
	v_pk_mul_f32 v[98:99], v[60:61], v[60:61]
	v_add_f32_e32 v70, v98, v99
	v_pk_mul_f32 v[98:99], v[62:63], v[62:63]
	v_add_f32_e32 v71, v98, v99
	ds_bpermute_b32 v72, v91, v64
	ds_bpermute_b32 v73, v91, v65
	ds_bpermute_b32 v74, v91, v66
	ds_bpermute_b32 v75, v91, v67
	ds_bpermute_b32 v76, v91, v68
	ds_bpermute_b32 v77, v91, v69
	ds_bpermute_b32 v78, v91, v70
	ds_bpermute_b32 v79, v91, v71
	s_waitcnt lgkmcnt(0)
	v_add_f32_e32 v64, v64, v72
	v_add_f32_e32 v65, v65, v73
	v_add_f32_e32 v66, v66, v74
	v_add_f32_e32 v67, v67, v75
	v_add_f32_e32 v68, v68, v76
	v_add_f32_e32 v69, v69, v77
	v_add_f32_e32 v70, v70, v78
	v_add_f32_e32 v71, v71, v79
	ds_bpermute_b32 v72, v92, v64
	ds_bpermute_b32 v73, v92, v65
	ds_bpermute_b32 v74, v92, v66
	ds_bpermute_b32 v75, v92, v67
	ds_bpermute_b32 v76, v92, v68
	ds_bpermute_b32 v77, v92, v69
	ds_bpermute_b32 v78, v92, v70
	ds_bpermute_b32 v79, v92, v71
	s_waitcnt lgkmcnt(0)
	v_add_f32_e32 v64, v64, v72
	v_add_f32_e32 v65, v65, v73
	v_add_f32_e32 v66, v66, v74
	v_add_f32_e32 v67, v67, v75
	v_add_f32_e32 v68, v68, v76
	v_add_f32_e32 v69, v69, v77
	v_add_f32_e32 v70, v70, v78
	v_add_f32_e32 v71, v71, v79
	ds_bpermute_b32 v72, v93, v64
	ds_bpermute_b32 v73, v93, v65
	ds_bpermute_b32 v74, v93, v66
	ds_bpermute_b32 v75, v93, v67
	ds_bpermute_b32 v76, v93, v68
	ds_bpermute_b32 v77, v93, v69
	ds_bpermute_b32 v78, v93, v70
	ds_bpermute_b32 v79, v93, v71
	s_waitcnt lgkmcnt(0)
	v_add_f32_e32 v64, v64, v72
	v_add_f32_e32 v65, v65, v73
	v_add_f32_e32 v66, v66, v74
	v_add_f32_e32 v67, v67, v75
	v_add_f32_e32 v68, v68, v76
	v_add_f32_e32 v69, v69, v77
	v_add_f32_e32 v70, v70, v78
	v_add_f32_e32 v71, v71, v79
	ds_bpermute_b32 v72, v94, v64
	ds_bpermute_b32 v73, v94, v65
	ds_bpermute_b32 v74, v94, v66
	ds_bpermute_b32 v75, v94, v67
	ds_bpermute_b32 v76, v94, v68
	ds_bpermute_b32 v77, v94, v69
	ds_bpermute_b32 v78, v94, v70
	ds_bpermute_b32 v79, v94, v71
	s_waitcnt lgkmcnt(0)
	v_add_f32_e32 v64, v64, v72
	v_add_f32_e32 v65, v65, v73
	v_add_f32_e32 v66, v66, v74
	v_add_f32_e32 v67, v67, v75
	v_add_f32_e32 v68, v68, v76
	v_add_f32_e32 v69, v69, v77
	v_add_f32_e32 v70, v70, v78
	v_add_f32_e32 v71, v71, v79
	ds_bpermute_b32 v72, v95, v64
	ds_bpermute_b32 v73, v95, v65
	ds_bpermute_b32 v74, v95, v66
	ds_bpermute_b32 v75, v95, v67
	ds_bpermute_b32 v76, v95, v68
	ds_bpermute_b32 v77, v95, v69
	ds_bpermute_b32 v78, v95, v70
	ds_bpermute_b32 v79, v95, v71
	s_waitcnt lgkmcnt(0)
	v_add_f32_e32 v64, v64, v72
	v_add_f32_e32 v65, v65, v73
	v_add_f32_e32 v66, v66, v74
	v_add_f32_e32 v67, v67, v75
	v_add_f32_e32 v68, v68, v76
	v_add_f32_e32 v69, v69, v77
	v_add_f32_e32 v70, v70, v78
	v_add_f32_e32 v71, v71, v79
	ds_bpermute_b32 v72, v96, v64
	ds_bpermute_b32 v73, v96, v65
	ds_bpermute_b32 v74, v96, v66
	ds_bpermute_b32 v75, v96, v67
	ds_bpermute_b32 v76, v96, v68
	ds_bpermute_b32 v77, v96, v69
	ds_bpermute_b32 v78, v96, v70
	ds_bpermute_b32 v79, v96, v71
	s_waitcnt lgkmcnt(0)
	v_add_f32_e32 v64, v64, v72
	v_add_f32_e32 v65, v65, v73
	v_add_f32_e32 v66, v66, v74
	v_add_f32_e32 v67, v67, v75
	v_add_f32_e32 v68, v68, v76
	v_add_f32_e32 v69, v69, v77
	v_add_f32_e32 v70, v70, v78
	v_add_f32_e32 v71, v71, v79
	v_fmamk_f32 v64, v64, 0x3c000000, v195
	v_cmp_gt_f32_e32 vcc, s67, v64
	v_mul_f32_e32 v72, 0x4b800000, v64
	s_nop 0
	v_cndmask_b32_e32 v64, v64, v72, vcc
	v_rsq_f32_e32 v64, v64
	s_nop 0
	v_mul_f32_e32 v72, 0x45800000, v64
	v_cndmask_b32_e32 v64, v64, v72, vcc
	v_fmamk_f32 v65, v65, 0x3c000000, v195
	v_cmp_gt_f32_e32 vcc, s67, v65
	v_mul_f32_e32 v73, 0x4b800000, v65
	s_nop 0
	v_cndmask_b32_e32 v65, v65, v73, vcc
	v_rsq_f32_e32 v65, v65
	s_nop 0
	v_mul_f32_e32 v73, 0x45800000, v65
	v_cndmask_b32_e32 v65, v65, v73, vcc
	v_fmamk_f32 v66, v66, 0x3c000000, v195
	v_cmp_gt_f32_e32 vcc, s67, v66
	v_mul_f32_e32 v74, 0x4b800000, v66
	s_nop 0
	v_cndmask_b32_e32 v66, v66, v74, vcc
	v_rsq_f32_e32 v66, v66
	s_nop 0
	v_mul_f32_e32 v74, 0x45800000, v66
	v_cndmask_b32_e32 v66, v66, v74, vcc
	v_fmamk_f32 v67, v67, 0x3c000000, v195
	v_cmp_gt_f32_e32 vcc, s67, v67
	v_mul_f32_e32 v75, 0x4b800000, v67
	s_nop 0
	v_cndmask_b32_e32 v67, v67, v75, vcc
	v_rsq_f32_e32 v67, v67
	s_nop 0
	v_mul_f32_e32 v75, 0x45800000, v67
	v_cndmask_b32_e32 v67, v67, v75, vcc
	v_fmamk_f32 v68, v68, 0x3c000000, v195
	v_cmp_gt_f32_e32 vcc, s67, v68
	v_mul_f32_e32 v76, 0x4b800000, v68
	s_nop 0
	v_cndmask_b32_e32 v68, v68, v76, vcc
	v_rsq_f32_e32 v68, v68
	s_nop 0
	v_mul_f32_e32 v76, 0x45800000, v68
	v_cndmask_b32_e32 v68, v68, v76, vcc
	v_fmamk_f32 v69, v69, 0x3c000000, v195
	v_cmp_gt_f32_e32 vcc, s67, v69
	v_mul_f32_e32 v77, 0x4b800000, v69
	s_nop 0
	v_cndmask_b32_e32 v69, v69, v77, vcc
	v_rsq_f32_e32 v69, v69
	s_nop 0
	v_mul_f32_e32 v77, 0x45800000, v69
	v_cndmask_b32_e32 v69, v69, v77, vcc
	v_fmamk_f32 v70, v70, 0x3c000000, v195
	v_cmp_gt_f32_e32 vcc, s67, v70
	v_mul_f32_e32 v78, 0x4b800000, v70
	s_nop 0
	v_cndmask_b32_e32 v70, v70, v78, vcc
	v_rsq_f32_e32 v70, v70
	s_nop 0
	v_mul_f32_e32 v78, 0x45800000, v70
	v_cndmask_b32_e32 v70, v70, v78, vcc
	v_fmamk_f32 v71, v71, 0x3c000000, v195
	v_cmp_gt_f32_e32 vcc, s67, v71
	v_mul_f32_e32 v79, 0x4b800000, v71
	s_nop 0
	v_cndmask_b32_e32 v71, v71, v79, vcc
	v_rsq_f32_e32 v71, v71
	s_nop 0
	v_mul_f32_e32 v79, 0x45800000, v71
	v_cndmask_b32_e32 v71, v71, v79, vcc
	s_waitcnt vmcnt(0)
	v_mul_f32_e32 v48, v48, v64
	v_mul_f32_e32 v49, v49, v64
	v_pk_mul_f32 v[48:49], v[234:235], v[48:49]
	v_lshlrev_b32_e32 v72, 16, v224
	v_and_b32_e32 v224, 0xffff0000, v224
	v_mul_f32_e32 v48, v48, v72
	v_mul_f32_e32 v49, v49, v224
	v_cvt_pk_bf16_f32 v72, v48, v49
	global_store_dword v3, v72, s[98:99]
	v_mul_f32_e32 v50, v50, v65
	v_mul_f32_e32 v51, v51, v65
	v_pk_mul_f32 v[50:51], v[234:235], v[50:51]
	v_lshlrev_b32_e32 v73, 16, v225
	v_and_b32_e32 v225, 0xffff0000, v225
	v_mul_f32_e32 v50, v50, v73
	v_mul_f32_e32 v51, v51, v225
	v_cvt_pk_bf16_f32 v73, v50, v51
	global_store_dword v3, v73, s[98:99] offset:2048
	s_add_u32 s98, s98, 0x1000
	s_addc_u32 s99, s99, 0
	v_mul_f32_e32 v52, v52, v66
	v_mul_f32_e32 v53, v53, v66
	v_pk_mul_f32 v[52:53], v[234:235], v[52:53]
	v_lshlrev_b32_e32 v74, 16, v226
	v_and_b32_e32 v226, 0xffff0000, v226
	v_mul_f32_e32 v52, v52, v74
	v_mul_f32_e32 v53, v53, v226
	v_cvt_pk_bf16_f32 v74, v52, v53
	global_store_dword v3, v74, s[98:99]
	v_mul_f32_e32 v54, v54, v67
	v_mul_f32_e32 v55, v55, v67
	v_pk_mul_f32 v[54:55], v[234:235], v[54:55]
	v_lshlrev_b32_e32 v75, 16, v227
	v_and_b32_e32 v227, 0xffff0000, v227
	v_mul_f32_e32 v54, v54, v75
	v_mul_f32_e32 v55, v55, v227
	v_cvt_pk_bf16_f32 v75, v54, v55
	global_store_dword v3, v75, s[98:99] offset:2048
	s_add_u32 s98, s98, 0x1000
	s_addc_u32 s99, s99, 0
	v_mul_f32_e32 v56, v56, v68
	v_mul_f32_e32 v57, v57, v68
	v_pk_mul_f32 v[56:57], v[234:235], v[56:57]
	v_lshlrev_b32_e32 v76, 16, v228
	v_and_b32_e32 v228, 0xffff0000, v228
	v_mul_f32_e32 v56, v56, v76
	v_mul_f32_e32 v57, v57, v228
	v_cvt_pk_bf16_f32 v76, v56, v57
	global_store_dword v3, v76, s[98:99]
	v_mul_f32_e32 v58, v58, v69
	v_mul_f32_e32 v59, v59, v69
	v_pk_mul_f32 v[58:59], v[234:235], v[58:59]
	v_lshlrev_b32_e32 v77, 16, v229
	v_and_b32_e32 v229, 0xffff0000, v229
	v_mul_f32_e32 v58, v58, v77
	v_mul_f32_e32 v59, v59, v229
	v_cvt_pk_bf16_f32 v77, v58, v59
	global_store_dword v3, v77, s[98:99] offset:2048
	s_add_u32 s98, s98, 0x1000
	s_addc_u32 s99, s99, 0
	v_mul_f32_e32 v60, v60, v70
	v_mul_f32_e32 v61, v61, v70
	v_pk_mul_f32 v[60:61], v[234:235], v[60:61]
	v_lshlrev_b32_e32 v78, 16, v230
	v_and_b32_e32 v230, 0xffff0000, v230
	v_mul_f32_e32 v60, v60, v78
	v_mul_f32_e32 v61, v61, v230
	v_cvt_pk_bf16_f32 v78, v60, v61
	global_store_dword v3, v78, s[98:99]
	v_mul_f32_e32 v62, v62, v71
	v_mul_f32_e32 v63, v63, v71
	v_pk_mul_f32 v[62:63], v[234:235], v[62:63]
	v_lshlrev_b32_e32 v79, 16, v231
	v_and_b32_e32 v231, 0xffff0000, v231
	v_mul_f32_e32 v62, v62, v79
	v_mul_f32_e32 v63, v63, v231
	v_cvt_pk_bf16_f32 v79, v62, v63
	global_store_dword v3, v79, s[98:99] offset:2048
	s_add_i32 s39, s39, s71
	s_cmpk_gt_i32 s39, 0x7ff
	s_barrier
	s_cbranch_scc1 .LBB0_494
.LBB0_449:
	s_ashr_i32 s2, s39, 10
	s_and_b32 s41, s39, 0x7f
	s_ashr_i32 s3, s2, 31
	v_mov_b32_e32 v23, v194
	s_lshl_b64 s[34:35], s[2:3], 13
	s_lshl_b32 s2, s41, 6
	s_bfe_u32 s42, s39, 0x30007
	v_readfirstlane_b32 s40, v23
	s_or_b32 s34, s34, s2
	s_lshr_b32 s90, s40, 6
	s_lshl_b32 s90, s90, 3
	s_add_u32 s90, s34, s90
	s_addc_u32 s91, s35, 0
	s_lshl_b64 s[90:91], s[90:91], 11
	s_add_u32 s90, s22, s90
	s_addc_u32 s91, s23, s91
	s_lshl_b32 s92, s42, 8
	v_and_b32_e32 v232, 63, v23
	v_lshlrev_b32_e32 v233, 3, v232
	v_lshl_or_b32 v232, v232, 2, s92
	global_load_dword v224, v232, s[90:91]
	global_load_dword v225, v232, s[90:91] offset:2048
	s_add_u32 s90, s90, 0x1000
	s_addc_u32 s91, s91, 0
	global_load_dword v226, v232, s[90:91]
	global_load_dword v227, v232, s[90:91] offset:2048
	s_add_u32 s90, s90, 0x1000
	s_addc_u32 s91, s91, 0
	global_load_dword v228, v232, s[90:91]
	global_load_dword v229, v232, s[90:91] offset:2048
	s_add_u32 s90, s90, 0x1000
	s_addc_u32 s91, s91, 0
	global_load_dword v230, v232, s[90:91]
	global_load_dword v231, v232, s[90:91] offset:2048
	global_load_dwordx2 v[234:235], v233, s[20:21]
	s_cmp_gt_u32 s40, 63
	v_and_b32_e32 v22, 63, v23
	s_cbranch_scc1 .LBB0_451
	v_or_b32_e32 v0, s34, v22
	v_mov_b32_e32 v1, s35
	v_lshlrev_b64 v[0:1], 6, v[0:1]
	v_lshl_add_u64 v[0:1], s[30:31], 0, v[0:1]
	s_lshl_b32 s86, s42, 2
	v_lshl_add_u64 v[0:1], v[0:1], 0, s[86:87]
	v_mov_b32_e32 v3, s86
	global_load_dword v2, v[0:1], off offset:32
	global_load_dword v4, v3, s[26:27]
	s_nop 0
	global_load_dword v0, v[0:1], off
	s_nop 0
	global_load_dword v1, v3, s[28:29]
	s_lshl_b32 s98, s39, 4
	s_add_u32 s98, s0, s98
	s_addc_u32 s99, s1, 0
	v_mov_b32_e32 v41, 0x18100000
	global_load_dword v42, v41, s[98:99] offset:8
	s_mov_b32 s2, 0x3f317218
	s_waitcnt vmcnt(2)
	v_add_f32_e32 v2, v2, v4
	s_waitcnt vmcnt(0)
	v_add_f32_e32 v1, v0, v1
	v_min_f32_e32 v0, 0, v2
	v_mul_f32_e64 v2, |v2|, s79
	v_exp_f32_e32 v4, v2
	s_nop 0
	v_add_f32_e32 v5, 1.0, v4
	v_add_f32_e32 v2, -1.0, v5
	v_sub_f32_e32 v3, v2, v5
	v_add_f32_e32 v3, 1.0, v3
	v_sub_f32_e32 v2, v4, v2
	v_add_f32_e32 v6, v2, v3
	v_frexp_mant_f32_e32 v2, v5
	v_cmp_gt_f32_e32 vcc, s85, v2
	v_cvt_f64_f32_e32 v[2:3], v5
	v_frexp_exp_i32_f64_e32 v2, v[2:3]
	v_subbrev_co_u32_e32 v2, vcc, 0, v2, vcc
	v_sub_u32_e32 v3, 0, v2
	v_ldexp_f32 v5, v5, v3
	v_ldexp_f32 v3, v6, v3
	v_add_f32_e32 v6, -1.0, v5
	v_add_f32_e32 v7, 1.0, v6
	v_sub_f32_e32 v7, v5, v7
	v_add_f32_e32 v7, v3, v7
	v_add_f32_e32 v8, v6, v7
	v_sub_f32_e32 v6, v8, v6
	v_sub_f32_e32 v6, v7, v6
	v_add_f32_e32 v7, 1.0, v5
	v_add_f32_e32 v9, -1.0, v7
	v_sub_f32_e32 v5, v5, v9
	v_add_f32_e32 v3, v3, v5
	v_add_f32_e32 v5, v7, v3
	v_sub_f32_e32 v7, v5, v7
	v_sub_f32_e32 v3, v3, v7
	v_rcp_f32_e32 v7, v5
	v_cvt_f32_i32_e32 v2, v2
	v_mul_f32_e32 v9, v8, v7
	v_mul_f32_e32 v10, v5, v9
	v_fma_f32 v11, v9, v5, -v10
	v_fmac_f32_e32 v11, v9, v3
	v_add_f32_e32 v12, v10, v11
	v_sub_f32_e32 v13, v8, v12
	v_sub_f32_e32 v8, v8, v13
	v_sub_f32_e32 v10, v12, v10
	v_sub_f32_e32 v8, v8, v12
	v_add_f32_e32 v6, v6, v8
	v_sub_f32_e32 v8, v10, v11
	v_add_f32_e32 v6, v8, v6
	v_add_f32_e32 v8, v13, v6
	v_mul_f32_e32 v10, v7, v8
	v_mul_f32_e32 v11, v5, v10
	v_fma_f32 v5, v10, v5, -v11
	v_fmac_f32_e32 v5, v10, v3
	v_sub_f32_e32 v3, v13, v8
	v_add_f32_e32 v3, v6, v3
	v_add_f32_e32 v6, v11, v5
	v_sub_f32_e32 v12, v8, v6
	v_sub_f32_e32 v8, v8, v12
	v_sub_f32_e32 v11, v6, v11
	v_sub_f32_e32 v6, v8, v6
	v_add_f32_e32 v3, v3, v6
	v_sub_f32_e32 v5, v11, v5
	v_add_f32_e32 v3, v5, v3
	v_add_f32_e32 v5, v9, v10
	v_add_f32_e32 v3, v12, v3
	v_sub_f32_e32 v6, v5, v9
	v_mul_f32_e32 v3, v7, v3
	v_sub_f32_e32 v6, v10, v6
	v_add_f32_e32 v3, v6, v3
	v_mul_f32_e32 v9, 0x3f317218, v2
	v_add_f32_e32 v6, v5, v3
	v_fma_f32 v10, v2, s2, -v9
	v_mul_f32_e32 v7, v6, v6
	v_fmac_f32_e32 v10, 0xb102e308, v2
	v_sub_f32_e32 v2, v6, v5
	v_fmamk_f32 v8, v7, 0x3e9b6dac, v200
	v_sub_f32_e32 v2, v3, v2
	v_add_f32_e32 v3, v9, v10
	v_fmaak_f32 v8, v7, v8, 0x3f2aaada
	v_sub_f32_e32 v5, v3, v9
	v_ldexp_f32 v9, v6, 1
	v_mul_f32_e32 v6, v6, v7
	v_mul_f32_e32 v6, v6, v8
	v_add_f32_e32 v7, v9, v6
	v_sub_f32_e32 v8, v7, v9
	v_ldexp_f32 v2, v2, 1
	v_sub_f32_e32 v6, v6, v8
	v_add_f32_e32 v2, v2, v6
	v_add_f32_e32 v6, v7, v2
	v_sub_f32_e32 v7, v6, v7
	v_sub_f32_e32 v2, v2, v7
	v_add_f32_e32 v7, v3, v6
	v_sub_f32_e32 v8, v7, v3
	v_sub_f32_e32 v9, v7, v8
	v_sub_f32_e32 v5, v10, v5
	v_sub_f32_e32 v3, v3, v9
	v_sub_f32_e32 v6, v6, v8
	v_add_f32_e32 v3, v6, v3
	v_add_f32_e32 v6, v5, v2
	v_sub_f32_e32 v8, v6, v5
	v_sub_f32_e32 v9, v6, v8
	v_sub_f32_e32 v5, v5, v9
	v_sub_f32_e32 v2, v2, v8
	v_add_f32_e32 v3, v6, v3
	v_add_f32_e32 v2, v2, v5
	v_add_f32_e32 v5, v7, v3
	v_sub_f32_e32 v6, v5, v7
	v_sub_f32_e32 v3, v3, v6
	v_add_f32_e32 v2, v2, v3
	s_mov_b32 s2, 0x7f800000
	v_add_f32_e32 v2, v5, v2
	v_cmp_neq_f32_e32 vcc, s2, v4
	s_mov_b32 s2, 0x33800000
	v_add_u32_e32 v3, -1, v201
	v_cndmask_b32_e32 v2, v202, v2, vcc
	v_cmp_ngt_f32_e32 vcc, -1.0, v4
	s_nop 1
	v_cndmask_b32_e32 v2, v203, v2, vcc
	v_cmp_neq_f32_e32 vcc, -1.0, v4
	s_nop 1
	v_cndmask_b32_e32 v2, v204, v2, vcc
	v_cmp_lt_f32_e64 vcc, |v4|, s2
	s_lshl_b32 s2, s39, 2
	s_ashr_i32 s3, s2, 31
	v_cndmask_b32_e32 v2, v2, v4, vcc
	v_sub_f32_e32 v0, v0, v2
	v_mov_b32_e32 v4, v0
	s_nop 1
	v_add_f32_dpp v4, v0, v4 row_shr:1 row_mask:0xf bank_mask:0xf
	v_add_f32_dpp v4, v0, v4 row_shr:2 row_mask:0xf bank_mask:0xf
	v_add_f32_dpp v4, v0, v4 row_shr:3 row_mask:0xf bank_mask:0xf
	s_nop 1
	v_add_f32_dpp v4, v4, v4 row_shr:4 row_mask:0xf bank_mask:0xe
	s_nop 1
	v_add_f32_dpp v4, v4, v4 row_shr:8 row_mask:0xf bank_mask:0xc
	s_nop 1
	v_add_f32_dpp v4, v4, v4 row_bcast:15 row_mask:0xa bank_mask:0xf
	s_nop 1
	v_add_f32_dpp v4, v4, v4 row_bcast:31 row_mask:0xc bank_mask:0xf
	v_mov_b32_e32 v0, v4
	v_sub_f32_e32 v1, v1, v0
	v_mov_b32_e32 v3, v1
	s_nop 1
	v_max_f32_dpp v3, v1, v3 row_shr:1 row_mask:0xf bank_mask:0xf
	v_max_f32_dpp v3, v1, v3 row_shr:2 row_mask:0xf bank_mask:0xf
	v_max_f32_dpp v3, v1, v3 row_shr:3 row_mask:0xf bank_mask:0xf
	s_nop 1
	v_max_f32_dpp v3, v3, v3 row_shr:4 row_mask:0xf bank_mask:0xe
	s_nop 1
	v_max_f32_dpp v3, v3, v3 row_shr:8 row_mask:0xf bank_mask:0xc
	s_nop 1
	v_max_f32_dpp v3, v3, v3 row_bcast:15 row_mask:0xa bank_mask:0xf
	s_nop 1
	v_max_f32_dpp v3, v3, v3 row_bcast:31 row_mask:0xc bank_mask:0xf
	v_mov_b32_e32 v2, v3
	v_max_f32_e32 v2, v2, v2
	s_waitcnt vmcnt(0)
	v_mov_b32_e32 v3, v42
	v_max_f32_e32 v4, v3, v3
	v_max_f32_e32 v2, v4, v2
	v_lshl_add_u32 v4, v22, 2, 0
	v_add_u32_e32 v4, 0x19200, v4
	ds_write2st64_b32 v4, v1, v2 offset1:1
	v_sub_f32_e32 v1, v3, v2
	v_add_f32_e32 v0, v0, v2
	v_mul_f32_e32 v1, 0x3fb8aa3b, v1
	v_mul_f32_e32 v0, 0xbfb8aa3b, v0
	v_exp_f32_e32 v1, v1
	v_exp_f32_e32 v0, v0
	ds_write2st64_b32 v4, v1, v0 offset0:2 offset1:3
